# attention: priority raise around every MFMA run incl. row-sum MFMAs
# baseline (speedup 1.0000x reference)
.LBB0_1062:
	s_mov_b32 s66, s64
	s_mov_b32 s67, s64
	s_mov_b32 s65, s64
	v_mov_b64_e32 v[134:135], s[66:67]
	v_mov_b64_e32 v[132:133], s[64:65]
	v_exp_f32_e32 v0, v0
	v_cvt_pk_bf16_f32 v128, v140, v141
	v_cvt_pk_bf16_f32 v129, v142, v143
	v_cvt_pk_bf16_f32 v130, v144, v145
	v_cvt_pk_bf16_f32 v131, v146, v147
	v_cvt_pk_bf16_f32 v124, v148, v149
	v_cvt_pk_bf16_f32 v125, v150, v151
	s_setprio 1
	v_mfma_f32_16x16x32_bf16 v[68:71], v[132:135], v[128:131], v[68:71]
	s_setprio 0
	v_cvt_pk_bf16_f32 v126, v152, v153
	v_cvt_pk_bf16_f32 v127, v154, v0
	s_and_b64 vcc, exec, s[56:57]
	s_mov_b64 s[0:1], -1
	s_setprio 1
	v_mfma_f32_16x16x32_bf16 v[68:71], v[132:135], v[124:127], v[68:71]
	s_setprio 0
	s_cbranch_vccnz .LBB0_1192
	v_add3_u32 v0, v225, s5, -5
	v_max_i32_e32 v0, -7, v0
	v_cmp_ge_u32_e32 vcc, s20, v223
	v_cmp_lt_u32_e64 s[0:1], s20, v224
	v_add_u32_e32 v0, 7, v0
	v_readlane_b32 s20, v254, 35
	v_min_u32_e32 v0, 14, v0
	v_mov_b32_e32 v2, s20
	s_movk_i32 s20, 0x7c
	v_mad_u32_u24 v0, v0, s20, v2
	v_lshl_add_u32 v132, v207, 2, v0
	v_lshl_add_u32 v133, v208, 2, v0
	v_lshl_add_u32 v134, v209, 2, v0
	v_lshl_add_u32 v135, v210, 2, v0
	v_lshl_add_u32 v136, v211, 2, v0
	v_lshl_add_u32 v137, v212, 2, v0
	v_lshl_add_u32 v138, v213, 2, v0
	v_lshl_add_u32 v139, v214, 2, v0
	v_lshl_add_u32 v140, v215, 2, v0
	v_lshl_add_u32 v141, v216, 2, v0
	v_lshl_add_u32 v142, v217, 2, v0
	v_lshl_add_u32 v143, v218, 2, v0
	v_lshl_add_u32 v144, v219, 2, v0
	v_lshl_add_u32 v145, v220, 2, v0
	v_lshl_add_u32 v146, v221, 2, v0
	v_lshl_add_u32 v147, v222, 2, v0
	ds_read_b32 v132, v132 offset:60
	ds_read_b32 v133, v133 offset:60
	ds_read_b32 v134, v134 offset:60
	ds_read_b32 v135, v135 offset:60
	ds_read_b32 v136, v136
	ds_read_b32 v137, v137
	ds_read_b32 v138, v138
	ds_read_b32 v139, v139
	ds_read_b32 v140, v140
	ds_read_b32 v141, v141
	ds_read_b32 v142, v142
	ds_read_b32 v143, v143
	ds_read_b32 v144, v144
	ds_read_b32 v145, v145
	ds_read_b32 v146, v146
	ds_read_b32 v147, v147
	s_and_b64 s[0:1], s[0:1], vcc
	v_mov_b32_e32 v0, 0xff800000
	s_and_b64 s[58:59], s[40:41], s[0:1]
	s_waitcnt lgkmcnt(0)
	v_fmac_f32_e32 v132, 0x3e38aa3b, v108
	v_fmac_f32_e32 v133, 0x3e38aa3b, v109
	v_fmac_f32_e32 v134, 0x3e38aa3b, v110
	v_fmac_f32_e32 v135, 0x3e38aa3b, v111
	v_fmac_f32_e32 v136, 0x3e38aa3b, v112
	v_fmac_f32_e32 v137, 0x3e38aa3b, v113
	v_fmac_f32_e32 v138, 0x3e38aa3b, v114
	v_fmac_f32_e32 v139, 0x3e38aa3b, v115
	v_fmac_f32_e32 v140, 0x3e38aa3b, v116
	v_fmac_f32_e32 v141, 0x3e38aa3b, v117
	v_fmac_f32_e32 v142, 0x3e38aa3b, v118
	v_fmac_f32_e32 v143, 0x3e38aa3b, v119
	v_fmac_f32_e32 v144, 0x3e38aa3b, v120
	v_fmac_f32_e32 v145, 0x3e38aa3b, v121
	v_fmac_f32_e32 v146, 0x3e38aa3b, v122
	v_fmac_f32_e32 v147, 0x3e38aa3b, v123
	s_and_b64 s[66:67], s[42:43], s[0:1]
	v_cndmask_b32_e64 v132, v0, v132, s[58:59]
	s_and_b64 s[58:59], s[44:45], s[0:1]
	v_cndmask_b32_e64 v133, v0, v133, s[66:67]
	s_and_b64 s[66:67], s[46:47], s[0:1]
	v_cndmask_b32_e64 v134, v0, v134, s[58:59]
	s_and_b64 s[58:59], s[90:91], s[0:1]
	v_cndmask_b32_e64 v135, v0, v135, s[66:67]
	s_and_b64 s[66:67], s[8:9], s[0:1]
	v_cndmask_b32_e64 v136, v0, v136, s[58:59]
	s_and_b64 s[58:59], s[88:89], s[0:1]
	v_cndmask_b32_e64 v137, v0, v137, s[66:67]
	s_and_b64 s[66:67], s[94:95], s[0:1]
	v_cndmask_b32_e64 v138, v0, v138, s[58:59]
	s_and_b64 s[58:59], s[96:97], s[0:1]
	v_cndmask_b32_e64 v139, v0, v139, s[66:67]
	s_and_b64 s[66:67], s[84:85], s[0:1]
	v_cndmask_b32_e64 v140, v0, v140, s[58:59]
	s_and_b64 s[58:59], s[18:19], s[0:1]
	v_cndmask_b32_e64 v141, v0, v141, s[66:67]
	s_and_b64 s[66:67], s[62:63], s[0:1]
	v_cndmask_b32_e64 v142, v0, v142, s[58:59]
	s_and_b64 s[58:59], s[48:49], s[0:1]
	v_cndmask_b32_e64 v143, v0, v143, s[66:67]
	s_and_b64 s[66:67], s[50:51], s[0:1]
	v_cndmask_b32_e64 v144, v0, v144, s[58:59]
	s_and_b64 s[58:59], s[52:53], s[0:1]
	v_cndmask_b32_e64 v145, v0, v145, s[66:67]
	s_and_b64 s[66:67], s[54:55], s[0:1]
	v_cndmask_b32_e64 v146, v0, v146, s[58:59]
	s_nop 0
	v_cndmask_b32_e64 v147, v0, v147, s[66:67]
	v_max3_f32 v0, v165, v132, v133
	v_max3_f32 v0, v0, v134, v135
	v_max3_f32 v0, v0, v136, v137
	v_max3_f32 v0, v0, v138, v139
	v_max3_f32 v0, v0, v140, v141
	v_max3_f32 v0, v0, v142, v143
	v_max3_f32 v0, v0, v144, v145
	v_max3_f32 v0, v0, v146, v147

.LBB0_1148:
	s_mov_b32 s66, s64
	s_mov_b32 s67, s64
	s_mov_b32 s65, s64
	v_mov_b64_e32 v[134:135], s[66:67]
	v_mov_b64_e32 v[132:133], s[64:65]
	v_exp_f32_e32 v0, v0
	v_cvt_pk_bf16_f32 v128, v140, v141
	v_cvt_pk_bf16_f32 v129, v142, v143
	v_cvt_pk_bf16_f32 v130, v144, v145
	v_cvt_pk_bf16_f32 v131, v146, v147
	v_cvt_pk_bf16_f32 v124, v148, v149
	v_cvt_pk_bf16_f32 v125, v150, v151
	s_setprio 1
	v_mfma_f32_16x16x32_bf16 v[68:71], v[132:135], v[128:131], v[68:71]
	s_setprio 0
	v_cvt_pk_bf16_f32 v126, v152, v153
	v_cvt_pk_bf16_f32 v127, v154, v0
	s_and_b64 vcc, exec, s[56:57]
	s_mov_b64 s[0:1], -1
	s_setprio 1
	v_mfma_f32_16x16x32_bf16 v[68:71], v[132:135], v[124:127], v[68:71]
	s_setprio 0
	s_cbranch_vccnz .LBB0_1198
	v_add3_u32 v0, v225, s5, -4
	v_max_i32_e32 v0, -7, v0
	v_cmp_ge_u32_e32 vcc, s20, v223
	v_cmp_lt_u32_e64 s[0:1], s20, v224
	v_add_u32_e32 v0, 7, v0
	v_readlane_b32 s20, v254, 35
	v_min_u32_e32 v0, 14, v0
	v_mov_b32_e32 v2, s20
	s_movk_i32 s20, 0x7c
	v_mad_u32_u24 v0, v0, s20, v2
	v_lshl_add_u32 v132, v207, 2, v0
	v_lshl_add_u32 v133, v208, 2, v0
	v_lshl_add_u32 v134, v209, 2, v0
	v_lshl_add_u32 v135, v210, 2, v0
	v_lshl_add_u32 v136, v211, 2, v0
	v_lshl_add_u32 v137, v212, 2, v0
	v_lshl_add_u32 v138, v213, 2, v0
	v_lshl_add_u32 v139, v214, 2, v0
	v_lshl_add_u32 v140, v215, 2, v0
	v_lshl_add_u32 v141, v216, 2, v0
	v_lshl_add_u32 v142, v217, 2, v0
	v_lshl_add_u32 v143, v218, 2, v0
	v_lshl_add_u32 v144, v219, 2, v0
	v_lshl_add_u32 v145, v220, 2, v0
	v_lshl_add_u32 v146, v221, 2, v0
	v_lshl_add_u32 v147, v222, 2, v0
	ds_read_b32 v132, v132 offset:60
	ds_read_b32 v133, v133 offset:60
	ds_read_b32 v134, v134 offset:60
	ds_read_b32 v135, v135 offset:60
	ds_read_b32 v136, v136
	ds_read_b32 v137, v137
	ds_read_b32 v138, v138
	ds_read_b32 v139, v139
	ds_read_b32 v140, v140
	ds_read_b32 v141, v141
	ds_read_b32 v142, v142
	ds_read_b32 v143, v143
	ds_read_b32 v144, v144
	ds_read_b32 v145, v145
	ds_read_b32 v146, v146
	ds_read_b32 v147, v147
	s_and_b64 s[0:1], s[0:1], vcc
	v_mov_b32_e32 v0, 0xff800000
	s_and_b64 s[58:59], s[40:41], s[0:1]
	s_waitcnt lgkmcnt(0)
	v_fmac_f32_e32 v132, 0x3e38aa3b, v108
	v_fmac_f32_e32 v133, 0x3e38aa3b, v109
	v_fmac_f32_e32 v134, 0x3e38aa3b, v110
	v_fmac_f32_e32 v135, 0x3e38aa3b, v111
	v_fmac_f32_e32 v136, 0x3e38aa3b, v112
	v_fmac_f32_e32 v137, 0x3e38aa3b, v113
	v_fmac_f32_e32 v138, 0x3e38aa3b, v114
	v_fmac_f32_e32 v139, 0x3e38aa3b, v115
	v_fmac_f32_e32 v140, 0x3e38aa3b, v116
	v_fmac_f32_e32 v141, 0x3e38aa3b, v117
	v_fmac_f32_e32 v142, 0x3e38aa3b, v118
	v_fmac_f32_e32 v143, 0x3e38aa3b, v119
	v_fmac_f32_e32 v144, 0x3e38aa3b, v120
	v_fmac_f32_e32 v145, 0x3e38aa3b, v121
	v_fmac_f32_e32 v146, 0x3e38aa3b, v122
	v_fmac_f32_e32 v147, 0x3e38aa3b, v123
	s_and_b64 s[66:67], s[42:43], s[0:1]
	v_cndmask_b32_e64 v132, v0, v132, s[58:59]
	s_and_b64 s[58:59], s[44:45], s[0:1]
	v_cndmask_b32_e64 v133, v0, v133, s[66:67]
	s_and_b64 s[66:67], s[46:47], s[0:1]
	v_cndmask_b32_e64 v134, v0, v134, s[58:59]
	s_and_b64 s[58:59], s[90:91], s[0:1]
	v_cndmask_b32_e64 v135, v0, v135, s[66:67]
	s_and_b64 s[66:67], s[8:9], s[0:1]
	v_cndmask_b32_e64 v136, v0, v136, s[58:59]
	s_and_b64 s[58:59], s[88:89], s[0:1]
	v_cndmask_b32_e64 v137, v0, v137, s[66:67]
	s_and_b64 s[66:67], s[94:95], s[0:1]
	v_cndmask_b32_e64 v138, v0, v138, s[58:59]
	s_and_b64 s[58:59], s[96:97], s[0:1]
	v_cndmask_b32_e64 v139, v0, v139, s[66:67]
	s_and_b64 s[66:67], s[84:85], s[0:1]
	v_cndmask_b32_e64 v140, v0, v140, s[58:59]
	s_and_b64 s[58:59], s[18:19], s[0:1]
	v_cndmask_b32_e64 v141, v0, v141, s[66:67]
	s_and_b64 s[66:67], s[62:63], s[0:1]
	v_cndmask_b32_e64 v142, v0, v142, s[58:59]
	s_and_b64 s[58:59], s[48:49], s[0:1]
	v_cndmask_b32_e64 v143, v0, v143, s[66:67]
	s_and_b64 s[66:67], s[50:51], s[0:1]
	v_cndmask_b32_e64 v144, v0, v144, s[58:59]
	s_and_b64 s[58:59], s[52:53], s[0:1]
	v_cndmask_b32_e64 v145, v0, v145, s[66:67]
	s_and_b64 s[66:67], s[54:55], s[0:1]
	v_cndmask_b32_e64 v146, v0, v146, s[58:59]
	s_nop 0
	v_cndmask_b32_e64 v147, v0, v147, s[66:67]
	v_max3_f32 v0, v165, v132, v133
	v_max3_f32 v0, v0, v134, v135
	v_max3_f32 v0, v0, v136, v137
	v_max3_f32 v0, v0, v138, v139
	v_max3_f32 v0, v0, v140, v141
	v_max3_f32 v0, v0, v142, v143
	v_max3_f32 v0, v0, v144, v145
	v_max3_f32 v0, v0, v146, v147

.LBB0_1279:
	v_fma_f32 v132, v132, s35, -v2
	v_fma_f32 v133, v133, s35, -v2
	v_fma_f32 v134, v134, s35, -v2
	v_fma_f32 v135, v135, s35, -v2
	v_fma_f32 v124, v124, s35, -v2
	v_fma_f32 v3, v136, s35, -v2
	v_fma_f32 v136, v137, s35, -v2
	v_fma_f32 v137, v138, s35, -v2
	v_fma_f32 v138, v139, s35, -v2
	v_exp_f32_e32 v132, v132
	v_exp_f32_e32 v133, v133
	v_exp_f32_e32 v134, v134
	v_exp_f32_e32 v135, v135
	v_exp_f32_e32 v139, v124
	v_fma_f32 v124, v125, s35, -v2
	v_fma_f32 v128, v128, s35, -v2
	v_fma_f32 v129, v129, s35, -v2
	v_fma_f32 v130, v130, s35, -v2
	v_fma_f32 v131, v131, s35, -v2
	v_exp_f32_e32 v163, v124
	v_fma_f32 v124, v126, s35, -v2
	v_fma_f32 v2, v127, s35, -v2
	v_exp_f32_e32 v3, v3
	v_exp_f32_e32 v136, v136
	v_exp_f32_e32 v128, v128
	v_exp_f32_e32 v129, v129
	v_exp_f32_e32 v130, v130
	v_exp_f32_e32 v131, v131
	v_exp_f32_e32 v164, v124
	v_exp_f32_e32 v2, v2
	s_mov_b32 s66, s64
	s_mov_b32 s67, s64
	v_cvt_pk_bf16_f32 v126, v132, v133
	v_cvt_pk_bf16_f32 v127, v134, v135
	s_mov_b32 s65, s64
	v_mov_b64_e32 v[134:135], s[66:67]
	v_exp_f32_e32 v137, v137
	v_exp_f32_e32 v138, v138
	v_mov_b64_e32 v[132:133], s[64:65]
	v_cvt_pk_bf16_f32 v124, v3, v136
	v_cvt_pk_bf16_f32 v128, v128, v129
	v_cvt_pk_bf16_f32 v129, v130, v131
	v_cvt_pk_bf16_f32 v131, v164, v2
	v_max_f32_e32 v2, v121, v121
	v_max_f32_e32 v3, v120, v120
	v_max_f32_e32 v2, v3, v2
	v_max3_f32 v2, v2, v122, v123
	v_cvt_pk_bf16_f32 v125, v137, v138
	v_max3_f32 v2, v2, v116, v117
	v_max3_f32 v2, v2, v118, v119
	s_setprio 1
	v_mfma_f32_16x16x32_bf16 v[36:39], v[132:135], v[124:127], v[36:39]
	s_setprio 0
	v_max3_f32 v2, v2, v112, v113
	v_max3_f32 v2, v2, v114, v115
	v_cvt_pk_bf16_f32 v130, v139, v163
	v_max3_f32 v2, v2, v108, v109
	v_max3_f32 v2, v2, v110, v111
	s_setprio 1
	v_mfma_f32_16x16x32_bf16 v[36:39], v[132:135], v[128:131], v[36:39]
	s_setprio 0
	v_mul_f32_e32 v2, 0x3e38aa3b, v2
	v_max_f32_e32 v3, v159, v159
	v_max_f32_e32 v2, v3, v2
	v_cmp_gt_f32_e32 vcc, v2, v159
	s_cbranch_vccz .LBB0_1284
	v_cmp_lt_i32_e32 vcc, v175, v173
	s_nop 1
	v_cndmask_b32_e32 v3, v172, v175, vcc
	v_lshlrev_b32_e32 v3, 2, v3
	ds_bpermute_b32 v3, v3, v2
	v_cmp_lt_i32_e32 vcc, v174, v173
	v_max_f32_e32 v2, v2, v2
	s_waitcnt lgkmcnt(0)
	v_max_f32_e32 v3, v3, v3
	v_cndmask_b32_e32 v132, v172, v174, vcc
	v_max_f32_e32 v2, v2, v3
	v_lshlrev_b32_e32 v3, 2, v132
	ds_bpermute_b32 v3, v3, v2
	s_waitcnt lgkmcnt(0)
	v_max_f32_e32 v3, v3, v3
	v_max_f32_e32 v133, v2, v3
	v_sub_f32_e32 v2, v159, v133
	v_exp_f32_e32 v132, v2
	v_mov_b32_e32 v159, v133
	v_mov_b64_e32 v[2:3], v[158:159]
	v_pk_mul_f32 v[62:63], v[62:63], v[132:133] op_sel_hi:[1,0]
	v_pk_mul_f32 v[60:61], v[60:61], v[132:133] op_sel_hi:[1,0]
	v_pk_mul_f32 v[50:51], v[50:51], v[132:133] op_sel_hi:[1,0]
	v_pk_mul_f32 v[48:49], v[48:49], v[132:133] op_sel_hi:[1,0]
	v_pk_mul_f32 v[46:47], v[46:47], v[132:133] op_sel_hi:[1,0]
	v_pk_mul_f32 v[44:45], v[44:45], v[132:133] op_sel_hi:[1,0]
	v_pk_mul_f32 v[42:43], v[42:43], v[132:133] op_sel_hi:[1,0]
	v_pk_mul_f32 v[40:41], v[40:41], v[132:133] op_sel_hi:[1,0]
	v_pk_mul_f32 v[66:67], v[66:67], v[132:133] op_sel_hi:[1,0]
	v_pk_mul_f32 v[64:65], v[64:65], v[132:133] op_sel_hi:[1,0]
	s_branch .LBB0_1285

.LBB0_1282:
	v_fma_f32 v132, v132, s35, -v2
	v_fma_f32 v133, v133, s35, -v2
	v_fma_f32 v134, v134, s35, -v2
	v_fma_f32 v135, v135, s35, -v2
	v_fma_f32 v124, v124, s35, -v2
	v_fma_f32 v0, v136, s35, -v2
	v_fma_f32 v136, v138, s35, -v2
	v_exp_f32_e32 v132, v132
	v_exp_f32_e32 v133, v133
	v_exp_f32_e32 v134, v134
	v_exp_f32_e32 v135, v135
	v_exp_f32_e32 v138, v124
	v_fma_f32 v124, v125, s35, -v2
	v_fma_f32 v3, v137, s35, -v2
	v_fma_f32 v137, v139, s35, -v2
	v_fma_f32 v128, v128, s35, -v2
	v_fma_f32 v129, v129, s35, -v2
	v_fma_f32 v130, v130, s35, -v2
	v_fma_f32 v131, v131, s35, -v2
	v_exp_f32_e32 v139, v124
	v_fma_f32 v124, v126, s35, -v2
	v_fma_f32 v2, v127, s35, -v2
	v_exp_f32_e32 v0, v0
	v_exp_f32_e32 v3, v3
	v_exp_f32_e32 v128, v128
	v_exp_f32_e32 v129, v129
	v_exp_f32_e32 v130, v130
	v_exp_f32_e32 v131, v131
	v_exp_f32_e32 v149, v124
	v_exp_f32_e32 v2, v2
	s_mov_b32 s66, s64
	s_mov_b32 s67, s64
	v_cvt_pk_bf16_f32 v126, v132, v133
	v_cvt_pk_bf16_f32 v127, v134, v135
	s_mov_b32 s65, s64
	v_mov_b64_e32 v[134:135], s[66:67]
	v_exp_f32_e32 v136, v136
	v_exp_f32_e32 v137, v137
	v_mov_b64_e32 v[132:133], s[64:65]
	v_cvt_pk_bf16_f32 v124, v0, v3
	v_cvt_pk_bf16_f32 v128, v128, v129
	v_cvt_pk_bf16_f32 v129, v130, v131
	v_cvt_pk_bf16_f32 v131, v149, v2
	v_max_f32_e32 v0, v121, v121
	v_max_f32_e32 v2, v120, v120
	v_max_f32_e32 v0, v2, v0
	v_max3_f32 v0, v0, v122, v123
	v_cvt_pk_bf16_f32 v125, v136, v137
	v_max3_f32 v0, v0, v116, v117
	v_max3_f32 v0, v0, v118, v119
	s_setprio 1
	v_mfma_f32_16x16x32_bf16 v[36:39], v[132:135], v[124:127], v[36:39]
	s_setprio 0
	v_max3_f32 v0, v0, v112, v113
	v_max3_f32 v0, v0, v114, v115
	v_cvt_pk_bf16_f32 v130, v138, v139
	v_max3_f32 v0, v0, v108, v109
	v_max3_f32 v0, v0, v110, v111
	s_setprio 1
	v_mfma_f32_16x16x32_bf16 v[36:39], v[132:135], v[128:131], v[36:39]
	s_setprio 0
	v_mul_f32_e32 v0, 0x3e38aa3b, v0
	v_max_f32_e32 v2, v159, v159
	v_max_f32_e32 v0, v2, v0
	v_cmp_gt_f32_e32 vcc, v0, v159
	s_cbranch_vccz .LBB0_1290
	v_cmp_lt_i32_e32 vcc, v175, v173
	s_nop 1
	v_cndmask_b32_e32 v2, v172, v175, vcc
	v_lshlrev_b32_e32 v2, 2, v2
	ds_bpermute_b32 v2, v2, v0
	v_cmp_lt_i32_e32 vcc, v174, v173
	v_max_f32_e32 v0, v0, v0
	s_waitcnt lgkmcnt(0)
	v_max_f32_e32 v2, v2, v2
	v_cndmask_b32_e32 v3, v172, v174, vcc
	v_max_f32_e32 v0, v0, v2
	v_lshlrev_b32_e32 v2, 2, v3
	ds_bpermute_b32 v2, v2, v0
	s_waitcnt lgkmcnt(0)
	v_max_f32_e32 v2, v2, v2
	v_max_f32_e32 v132, v0, v2
	v_sub_f32_e32 v0, v159, v132
	v_exp_f32_e32 v0, v0
	v_mov_b32_e32 v159, v132
	v_mov_b64_e32 v[2:3], v[158:159]
	v_pk_mul_f32 v[62:63], v[62:63], v[0:1] op_sel_hi:[1,0]
	v_pk_mul_f32 v[60:61], v[60:61], v[0:1] op_sel_hi:[1,0]
	v_pk_mul_f32 v[50:51], v[50:51], v[0:1] op_sel_hi:[1,0]
	v_pk_mul_f32 v[48:49], v[48:49], v[0:1] op_sel_hi:[1,0]
	v_pk_mul_f32 v[46:47], v[46:47], v[0:1] op_sel_hi:[1,0]
	v_pk_mul_f32 v[44:45], v[44:45], v[0:1] op_sel_hi:[1,0]
	v_pk_mul_f32 v[42:43], v[42:43], v[0:1] op_sel_hi:[1,0]
	v_pk_mul_f32 v[40:41], v[40:41], v[0:1] op_sel_hi:[1,0]
	v_pk_mul_f32 v[66:67], v[66:67], v[0:1] op_sel_hi:[1,0]
	v_pk_mul_f32 v[64:65], v[64:65], v[0:1] op_sel_hi:[1,0]
	s_branch .LBB0_1291
